# v87 plus: meta-row rope task, three store-only vmcnt(0) waits removed (loads already complete at the loop-head wait)
# speedup vs baseline: 1.0041x; 1.0034x over previous
.LBB0_952:
	s_or_b64 exec, exec, s[18:19]
	s_waitcnt lgkmcnt(0)
	v_lshl_add_u64 v[18:19], v[4:5], 2, s[8:9]
	v_or_b32_e32 v21, s27, v0
	v_lshlrev_b32_e32 v148, 7, v21
	s_lshl_b64 s[14:15], s[16:17], 1
	s_and_b32 s17, s26, 0x100
	v_lshl_add_u64 v[4:5], v[4:5], 1, s[12:13]
	v_cvt_pk_bf16_f32 v20, v152, s0
	v_lshl_add_u64 v[18:19], s[10:11], 0, v[148:149]
	v_lshl_add_u64 v[18:19], v[18:19], 0, s[14:15]
	global_store_short v[18:19], v20, off
	v_add_u32_e32 v18, s17, v17
	s_and_b32 s17, s25, 0x60
	v_or3_b32 v18, v18, s17, v1
	s_mul_hi_i32 s17, s16, 0x4400
	s_mulk_i32 s16, 0x4400
	s_add_u32 s16, s23, s16
	s_addc_u32 s17, s24, s17
	v_lshlrev_b32_e32 v18, 2, v18
	s_lshl_b32 s18, s27, 2
	s_add_u32 s16, s16, s18
	s_addc_u32 s17, s17, 0
	v_lshlrev_b32_e32 v148, 2, v0
	s_add_i32 s20, s20, s84
	s_add_i32 s26, s26, s96
	v_mul_f32_e32 v19, v154, v154
	ds_bpermute_b32 v19, v9, v19
	s_waitcnt lgkmcnt(0)
	v_fmac_f32_e32 v19, v154, v154
	ds_bpermute_b32 v20, v10, v19
	s_waitcnt lgkmcnt(0)
	v_add_f32_e32 v19, v19, v20
	ds_bpermute_b32 v20, v11, v19
	s_waitcnt lgkmcnt(0)
	v_add_f32_e32 v19, v19, v20
	ds_bpermute_b32 v20, v12, v19
	s_waitcnt lgkmcnt(0)
	v_add_f32_e32 v19, v19, v20
	ds_bpermute_b32 v20, v13, v19
	s_waitcnt lgkmcnt(0)
	v_add_f32_e32 v19, v19, v20
	ds_bpermute_b32 v20, v14, v19
	s_waitcnt lgkmcnt(0)
	v_add_f32_e32 v19, v19, v20
	v_fmamk_f32 v19, v19, 0x3c800000, v207
	v_rsq_f32_e32 v19, v19
	s_nop 0
	v_mul_f32_e32 v18, v154, v19
	v_mul_f32_e32 v18, v7, v18
	v_cvt_pk_bf16_f32 v18, v18, s0
	global_store_short v[4:5], v18, off
	v_lshl_add_u64 v[4:5], s[16:17], 0, v[148:149]
	v_add_co_u32_e32 v4, vcc, s33, v4
	v_lshlrev_b32_e32 v148, 5, v21
	s_nop 0
	v_addc_co_u32_e32 v5, vcc, 0, v5, vcc
	v_cvt_pk_bf16_f32 v18, v158, s0
	v_lshl_add_u64 v[4:5], s[4:5], 0, v[148:149]
	v_lshl_add_u64 v[4:5], v[4:5], 0, s[14:15]
	v_readlane_b32 s14, v253, 54
	s_add_i32 s25, s25, s14
	s_cmpk_gt_i32 s20, 0x7f
	global_store_short v[4:5], v18, off
	s_cbranch_scc1 .LBB0_957
